# selected-block and window loops: softmax row-sum adds moved from the VALU segment into the PV MFMA shadow of the partner segment (four adds per MFMA gap, before the QK MFMAs overwrite the score regist
# speedup vs baseline: 1.0007x; 1.0007x over previous
; DI float fast_exp2(float x) { return __builtin_amdgcn_exp2f(x); }
; DI float xhalf_max(float x) { auto rr = __builtin_amdgcn_permlane32_swap(__float_as_uint(x), __float_as_uint(x), false, false); return fmaxf(__uint_as_float(rr[0]), __uint_as_float(rr[1])); }
; #define NEG_INF (-__builtin_inff())
; template <int DV>
; DI void attn_softmax_pv(f32x16& s0, f32x16& s1, float& m, f32x16& lv, f32x16 (&o)[DV / 32], const unsigned char* vb, int r, int h, bool on = true) {
;     s0 = s0 * SM_C; s1 = s1 * SM_C;
;     const f32x16 t = __builtin_elementwise_max(s0, s1);
;     float mx = fmaxf(fmaxf(fmaxf(t[0], t[1]), fmaxf(t[2], t[3])), fmaxf(fmaxf(t[4], t[5]), fmaxf(t[6], t[7])));
;     mx = fmaxf(mx, fmaxf(fmaxf(fmaxf(t[8], t[9]), fmaxf(t[10], t[11])), fmaxf(fmaxf(t[12], t[13]), fmaxf(t[14], t[15]))));
;     mx = on ? mx : NEG_INF;
;     mx = xhalf_max(mx);
;     if (!__all(mx - m <= SM_THR)) {
;         const float mn = fmaxf(m, mx);
;         const float alpha = fast_exp2(m - mn);
;         lv = lv * alpha; m = mn;
; #pragma unroll
;         for (int dt = 0; dt < DV / 32; ++dt) o[dt] = o[dt] * alpha;
;     }
;     const float msub = on ? m : __builtin_inff();
;     s0 = s0 - msub; s1 = s1 - msub;
; #pragma unroll
;     for (int i = 0; i < 16; ++i) { s0[i] = fast_exp2(s0[i]); s1[i] = fast_exp2(s1[i]); }
;     lv = lv + (s0 + s1);
;     bf16x8 pf[2][2]; pack_p(s0, s1, pf);
;     attn_pv<DV>(vb, pf, r, h, o);
; }
.Lns_nr:
	v_cndmask_b32_e64 v167, v201, v207, s[14:15]
	v_fma_f32 v98, v98, s70, -v167
	v_fma_f32 v99, v99, s70, -v167
	v_fma_f32 v100, v100, s70, -v167
	v_fma_f32 v101, v101, s70, -v167
	v_fma_f32 v102, v102, s70, -v167
	v_fma_f32 v103, v103, s70, -v167
	v_fma_f32 v104, v104, s70, -v167
	v_fma_f32 v105, v105, s70, -v167
	v_exp_f32_e32 v98, v98
	v_exp_f32_e32 v99, v99
	v_exp_f32_e32 v100, v100
	v_exp_f32_e32 v101, v101
	v_exp_f32_e32 v102, v102
	v_exp_f32_e32 v103, v103
	v_exp_f32_e32 v104, v104
	v_exp_f32_e32 v105, v105
	v_fma_f32 v106, v106, s70, -v167
	v_fma_f32 v107, v107, s70, -v167
	v_fma_f32 v108, v108, s70, -v167
	v_fma_f32 v109, v109, s70, -v167
	v_fma_f32 v110, v110, s70, -v167
	v_fma_f32 v111, v111, s70, -v167
	v_fma_f32 v112, v112, s70, -v167
	v_fma_f32 v113, v113, s70, -v167
	v_exp_f32_e32 v106, v106
	v_exp_f32_e32 v107, v107
	v_exp_f32_e32 v108, v108
	v_exp_f32_e32 v109, v109
	v_exp_f32_e32 v110, v110
	v_exp_f32_e32 v111, v111
	v_exp_f32_e32 v112, v112
	v_exp_f32_e32 v113, v113
	v_fma_f32 v82, v82, s70, -v167
	v_fma_f32 v83, v83, s70, -v167
	v_fma_f32 v84, v84, s70, -v167
	v_fma_f32 v85, v85, s70, -v167
	v_fma_f32 v86, v86, s70, -v167
	v_fma_f32 v87, v87, s70, -v167
	v_fma_f32 v88, v88, s70, -v167
	v_fma_f32 v89, v89, s70, -v167
	v_exp_f32_e32 v82, v82
	v_exp_f32_e32 v83, v83
	v_exp_f32_e32 v84, v84
	v_exp_f32_e32 v85, v85
	v_exp_f32_e32 v86, v86
	v_exp_f32_e32 v87, v87
	v_exp_f32_e32 v88, v88
	v_exp_f32_e32 v89, v89
	v_fma_f32 v90, v90, s70, -v167
	v_fma_f32 v91, v91, s70, -v167
	v_fma_f32 v92, v92, s70, -v167
	v_fma_f32 v93, v93, s70, -v167
	v_fma_f32 v94, v94, s70, -v167
	v_fma_f32 v95, v95, s70, -v167
	v_fma_f32 v96, v96, s70, -v167
	v_fma_f32 v97, v97, s70, -v167
	v_exp_f32_e32 v90, v90
	v_exp_f32_e32 v91, v91
	v_exp_f32_e32 v92, v92
	v_exp_f32_e32 v93, v93
	v_exp_f32_e32 v94, v94
	v_exp_f32_e32 v95, v95
	v_exp_f32_e32 v96, v96
	v_exp_f32_e32 v97, v97
	v_cvt_pk_bf16_f32 v208, v98, v99
	v_cvt_pk_bf16_f32 v209, v100, v101
	v_cvt_pk_bf16_f32 v210, v102, v103
	v_cvt_pk_bf16_f32 v211, v104, v105
	v_cvt_pk_bf16_f32 v212, v106, v107
	v_cvt_pk_bf16_f32 v213, v108, v109
	v_cvt_pk_bf16_f32 v214, v110, v111
	v_cvt_pk_bf16_f32 v215, v112, v113
	v_cvt_pk_bf16_f32 v216, v82, v83
	v_cvt_pk_bf16_f32 v217, v84, v85
	v_cvt_pk_bf16_f32 v218, v86, v87
	v_cvt_pk_bf16_f32 v219, v88, v89
	v_cvt_pk_bf16_f32 v220, v90, v91
	v_cvt_pk_bf16_f32 v221, v92, v93
	v_cvt_pk_bf16_f32 v222, v94, v95
	v_cvt_pk_bf16_f32 v223, v96, v97
.Lns_xdone:
	s_waitcnt lgkmcnt(0)
	s_barrier
	s_setprio 3
	s_add_i32 s26, s13, 1
	s_mov_b64 s[16:17], 0
	s_cmp_ge_u32 s26, s2
	s_cbranch_scc1 .Lns_y1

;     ...
;             const bool mine = (mysel >> j) & 1ull;
	v_lshrrev_b64 v[168:169], s8, v[124:125]
	v_and_b32_e32 v168, 1, v168
	v_cmp_ne_u32_e64 s[16:17], 0, v168

;     ...
;             const bool mine = (mysel >> j) & 1ull;
;             if (__ballot(mine) != 0ull) {
;                 f32x16 s0, s1; attn_scores(sb, qf, r, h, s0, s1);
.Lns_y1:
	v_add3_u32 v145, s18, v204, v180
	v_add3_u32 v144, s19, v204, v180
	s_cmp_eq_u64 s[14:15], 0
	s_cbranch_scc1 .Lns_noa
	s_cmp_eq_u64 s[16:17], 0
	s_cbranch_scc1 .Lns_pvonly

; #define MFMA(a, b, c) __builtin_amdgcn_mfma_f32_32x32x16_bf16((a), (b), (c), 0, 0, 0)
; DI void attn_scores(const unsigned char* kb, const bf16x8 (&qf)[4], int r, int h, f32x16& s0, f32x16& s1) {
; #pragma unroll
;     for (int i = 0; i < 16; ++i) { s0[i] = 0.f; s1[i] = 0.f; }
; #pragma unroll
;     for (int s = 0; s < 4; ++s) {
;         const bf16x8 k0 = *(const bf16x8*)(kb + r * KP + s * 32 + h * 16);
;         const bf16x8 k1 = *(const bf16x8*)(kb + (32 + r) * KP + s * 32 + h * 16);
;         s0 = MFMA(k0, qf[s], s0); s1 = MFMA(k1, qf[s], s1);
;     }
; }
; template <int DV>
; DI void attn_pv(const unsigned char* vb, const bf16x8 (&pf)[2][2], int r, int h, f32x16 (&o)[DV / 32]) {
; #pragma unroll
;     for (int dt = 0; dt < DV / 32; ++dt)
; #pragma unroll
;         for (int mt = 0; mt < 2; ++mt)
; #pragma unroll
;             for (int sp = 0; sp < 2; ++sp) {
;                 const bf16x8 vf = *(const bf16x8*)(vb + (dt * 32 + r) * VP + (2 * mt + sp) * 32 + h * 16);
;                 o[dt] = MFMA(vf, pf[mt][sp], o[dt]);
;             }
; }
	ds_read_b128 v[224:227], v145 offset:9216
	ds_read_b128 v[228:231], v145 offset:9248
	ds_read_b128 v[232:235], v145 offset:9280
	ds_read_b128 v[132:135], v145 offset:9312
	ds_read_b128 v[136:139], v145 offset:13824
	ds_read_b128 v[140:143], v145 offset:13856
	s_waitcnt lgkmcnt(5)
	v_mfma_f32_32x32x16_bf16 v[50:65], v[224:227], v[208:211], v[50:65]
	ds_read_b128 v[224:227], v145 offset:13888
	v_add_f32_e32 v98, v98, v82
	v_add_f32_e32 v99, v99, v83
	v_add_f32_e32 v66, v66, v98
	v_add_f32_e32 v100, v100, v84
	s_waitcnt lgkmcnt(5)
	v_mfma_f32_32x32x16_bf16 v[50:65], v[228:231], v[212:215], v[50:65]
	ds_read_b128 v[228:231], v145 offset:13920
	v_add_f32_e32 v67, v67, v99
	v_add_f32_e32 v101, v101, v85
	v_add_f32_e32 v68, v68, v100
	v_add_f32_e32 v102, v102, v86
	s_waitcnt lgkmcnt(5)
	v_mfma_f32_32x32x16_bf16 v[50:65], v[232:235], v[216:219], v[50:65]
	ds_read_b128 v[232:235], v144 offset:0
	v_add_f32_e32 v69, v69, v101
	v_add_f32_e32 v103, v103, v87
	v_add_f32_e32 v70, v70, v102
	v_add_f32_e32 v104, v104, v88
	s_waitcnt lgkmcnt(5)
	v_mfma_f32_32x32x16_bf16 v[50:65], v[132:135], v[220:223], v[50:65]
	ds_read_b128 v[132:135], v144 offset:4608
	v_add_f32_e32 v71, v71, v103
	v_add_f32_e32 v105, v105, v89
	v_add_f32_e32 v72, v72, v104
	v_add_f32_e32 v106, v106, v90
	s_waitcnt lgkmcnt(5)
	v_mfma_f32_32x32x16_bf16 v[34:49], v[136:139], v[208:211], v[34:49]
	ds_read_b128 v[136:139], v144 offset:32
	v_add_f32_e32 v73, v73, v105
	v_add_f32_e32 v107, v107, v91
	v_add_f32_e32 v74, v74, v106
	v_add_f32_e32 v108, v108, v92
	s_waitcnt lgkmcnt(5)
	v_mfma_f32_32x32x16_bf16 v[34:49], v[140:143], v[212:215], v[34:49]
	ds_read_b128 v[140:143], v144 offset:4640
	v_add_f32_e32 v75, v75, v107
	v_add_f32_e32 v109, v109, v93
	v_add_f32_e32 v76, v76, v108
	v_add_f32_e32 v110, v110, v94
	s_waitcnt lgkmcnt(5)
	v_mfma_f32_32x32x16_bf16 v[34:49], v[224:227], v[216:219], v[34:49]
	ds_read_b128 v[224:227], v144 offset:64
	v_add_f32_e32 v77, v77, v109
	v_add_f32_e32 v111, v111, v95
	v_add_f32_e32 v78, v78, v110
	v_add_f32_e32 v112, v112, v96
	s_waitcnt lgkmcnt(5)
	v_mfma_f32_32x32x16_bf16 v[34:49], v[228:231], v[220:223], v[34:49]
	ds_read_b128 v[228:231], v144 offset:4672
	v_add_f32_e32 v79, v79, v111
	v_add_f32_e32 v113, v113, v97
	v_add_f32_e32 v80, v80, v112
	v_add_f32_e32 v81, v81, v113
	s_waitcnt lgkmcnt(5)
	v_mfma_f32_32x32x16_bf16 v[98:113], v[232:235], v[146:149], 0
	ds_read_b128 v[232:235], v144 offset:96
	s_waitcnt lgkmcnt(5)
	v_mfma_f32_32x32x16_bf16 v[82:97], v[132:135], v[146:149], 0
	ds_read_b128 v[132:135], v144 offset:4704
	s_waitcnt lgkmcnt(5)
	v_mfma_f32_32x32x16_bf16 v[98:113], v[136:139], v[150:153], v[98:113]
	s_waitcnt lgkmcnt(4)
	v_mfma_f32_32x32x16_bf16 v[82:97], v[140:143], v[150:153], v[82:97]
	s_waitcnt lgkmcnt(3)
	v_mfma_f32_32x32x16_bf16 v[98:113], v[224:227], v[154:157], v[98:113]
	s_waitcnt lgkmcnt(2)
	v_mfma_f32_32x32x16_bf16 v[82:97], v[228:231], v[154:157], v[82:97]
	s_waitcnt lgkmcnt(1)
	v_mfma_f32_32x32x16_bf16 v[98:113], v[232:235], v[158:161], v[98:113]
	s_waitcnt lgkmcnt(0)
	v_mfma_f32_32x32x16_bf16 v[82:97], v[132:135], v[158:161], v[82:97]
	s_branch .Lns_stage
.Lns_pvonly:
	ds_read_b128 v[224:227], v145 offset:9216
	ds_read_b128 v[228:231], v145 offset:9248
	ds_read_b128 v[232:235], v145 offset:9280
	ds_read_b128 v[132:135], v145 offset:9312
	ds_read_b128 v[136:139], v145 offset:13824
	ds_read_b128 v[140:143], v145 offset:13856
	s_waitcnt lgkmcnt(5)
	v_mfma_f32_32x32x16_bf16 v[50:65], v[224:227], v[208:211], v[50:65]
	ds_read_b128 v[224:227], v145 offset:13888
	v_add_f32_e32 v98, v98, v82
	v_add_f32_e32 v99, v99, v83
	v_add_f32_e32 v66, v66, v98
	v_add_f32_e32 v100, v100, v84
	s_waitcnt lgkmcnt(5)
	v_mfma_f32_32x32x16_bf16 v[50:65], v[228:231], v[212:215], v[50:65]
	ds_read_b128 v[228:231], v145 offset:13920
	v_add_f32_e32 v67, v67, v99
	v_add_f32_e32 v101, v101, v85
	v_add_f32_e32 v68, v68, v100
	v_add_f32_e32 v102, v102, v86
	s_waitcnt lgkmcnt(5)
	v_mfma_f32_32x32x16_bf16 v[50:65], v[232:235], v[216:219], v[50:65]
	v_add_f32_e32 v69, v69, v101
	v_add_f32_e32 v103, v103, v87
	v_add_f32_e32 v70, v70, v102
	v_add_f32_e32 v104, v104, v88
	s_waitcnt lgkmcnt(4)
	v_mfma_f32_32x32x16_bf16 v[50:65], v[132:135], v[220:223], v[50:65]
	v_add_f32_e32 v71, v71, v103
	v_add_f32_e32 v105, v105, v89
	v_add_f32_e32 v72, v72, v104
	v_add_f32_e32 v106, v106, v90
	s_waitcnt lgkmcnt(3)
	v_mfma_f32_32x32x16_bf16 v[34:49], v[136:139], v[208:211], v[34:49]
	v_add_f32_e32 v73, v73, v105
	v_add_f32_e32 v107, v107, v91
	v_add_f32_e32 v74, v74, v106
	v_add_f32_e32 v108, v108, v92
	s_waitcnt lgkmcnt(2)
	v_mfma_f32_32x32x16_bf16 v[34:49], v[140:143], v[212:215], v[34:49]
	v_add_f32_e32 v75, v75, v107
	v_add_f32_e32 v109, v109, v93
	v_add_f32_e32 v76, v76, v108
	v_add_f32_e32 v110, v110, v94
	s_waitcnt lgkmcnt(1)
	v_mfma_f32_32x32x16_bf16 v[34:49], v[224:227], v[216:219], v[34:49]
	v_add_f32_e32 v77, v77, v109
	v_add_f32_e32 v111, v111, v95
	v_add_f32_e32 v78, v78, v110
	v_add_f32_e32 v112, v112, v96
	s_waitcnt lgkmcnt(0)
	v_mfma_f32_32x32x16_bf16 v[34:49], v[228:231], v[220:223], v[34:49]
	v_add_f32_e32 v79, v79, v111
	v_add_f32_e32 v113, v113, v97
	v_add_f32_e32 v80, v80, v112
	v_add_f32_e32 v81, v81, v113
	s_branch .Lns_stage

; DI float fast_exp2(float x) { return __builtin_amdgcn_exp2f(x); }
; DI float xhalf_max(float x) { auto rr = __builtin_amdgcn_permlane32_swap(__float_as_uint(x), __float_as_uint(x), false, false); return fmaxf(__uint_as_float(rr[0]), __uint_as_float(rr[1])); }
; #define NEG_INF (-__builtin_inff())
; template <int DV>
; DI void attn_softmax_pv(f32x16& s0, f32x16& s1, float& m, f32x16& lv, f32x16 (&o)[DV / 32], const unsigned char* vb, int r, int h, bool on = true) {
;     s0 = s0 * SM_C; s1 = s1 * SM_C;
;     const f32x16 t = __builtin_elementwise_max(s0, s1);
;     float mx = fmaxf(fmaxf(fmaxf(t[0], t[1]), fmaxf(t[2], t[3])), fmaxf(fmaxf(t[4], t[5]), fmaxf(t[6], t[7])));
;     mx = fmaxf(mx, fmaxf(fmaxf(fmaxf(t[8], t[9]), fmaxf(t[10], t[11])), fmaxf(fmaxf(t[12], t[13]), fmaxf(t[14], t[15]))));
;     mx = on ? mx : NEG_INF;
;     mx = xhalf_max(mx);
;     if (!__all(mx - m <= SM_THR)) {
;         const float mn = fmaxf(m, mx);
;         const float alpha = fast_exp2(m - mn);
;         lv = lv * alpha; m = mn;
; #pragma unroll
;         for (int dt = 0; dt < DV / 32; ++dt) o[dt] = o[dt] * alpha;
;     }
;     const float msub = on ? m : __builtin_inff();
;     s0 = s0 - msub; s1 = s1 - msub;
; #pragma unroll
;     for (int i = 0; i < 16; ++i) { s0[i] = fast_exp2(s0[i]); s1[i] = fast_exp2(s1[i]); }
;     lv = lv + (s0 + s1);
;     bf16x8 pf[2][2]; pack_p(s0, s1, pf);
;     attn_pv<DV>(vb, pf, r, h, o);
; }
.Lnw_nr:
	v_fma_f32 v130, v130, s70, -v211
	v_fma_f32 v131, v131, s70, -v211
	v_fma_f32 v132, v132, s70, -v211
	v_fma_f32 v133, v133, s70, -v211
	v_fma_f32 v134, v134, s70, -v211
	v_fma_f32 v135, v135, s70, -v211
	v_fma_f32 v136, v136, s70, -v211
	v_fma_f32 v137, v137, s70, -v211
	v_exp_f32_e32 v130, v130
	v_exp_f32_e32 v131, v131
	v_exp_f32_e32 v132, v132
	v_exp_f32_e32 v133, v133
	v_exp_f32_e32 v134, v134
	v_exp_f32_e32 v135, v135
	v_exp_f32_e32 v136, v136
	v_exp_f32_e32 v137, v137
	v_fma_f32 v138, v138, s70, -v211
	v_fma_f32 v139, v139, s70, -v211
	v_fma_f32 v140, v140, s70, -v211
	v_fma_f32 v141, v141, s70, -v211
	v_fma_f32 v142, v142, s70, -v211
	v_fma_f32 v143, v143, s70, -v211
	v_fma_f32 v144, v144, s70, -v211
	v_fma_f32 v145, v145, s70, -v211
	v_exp_f32_e32 v138, v138
	v_exp_f32_e32 v139, v139
	v_exp_f32_e32 v140, v140
	v_exp_f32_e32 v141, v141
	v_exp_f32_e32 v142, v142
	v_exp_f32_e32 v143, v143
	v_exp_f32_e32 v144, v144
	v_exp_f32_e32 v145, v145
	v_fma_f32 v114, v114, s70, -v211
	v_fma_f32 v115, v115, s70, -v211
	v_fma_f32 v116, v116, s70, -v211
	v_fma_f32 v117, v117, s70, -v211
	v_fma_f32 v118, v118, s70, -v211
	v_fma_f32 v119, v119, s70, -v211
	v_fma_f32 v120, v120, s70, -v211
	v_fma_f32 v121, v121, s70, -v211
	v_exp_f32_e32 v114, v114
	v_exp_f32_e32 v115, v115
	v_exp_f32_e32 v116, v116
	v_exp_f32_e32 v117, v117
	v_exp_f32_e32 v118, v118
	v_exp_f32_e32 v119, v119
	v_exp_f32_e32 v120, v120
	v_exp_f32_e32 v121, v121
	v_fma_f32 v122, v122, s70, -v211
	v_fma_f32 v123, v123, s70, -v211
	v_fma_f32 v124, v124, s70, -v211
	v_fma_f32 v125, v125, s70, -v211
	v_fma_f32 v126, v126, s70, -v211
	v_fma_f32 v127, v127, s70, -v211
	v_fma_f32 v128, v128, s70, -v211
	v_fma_f32 v129, v129, s70, -v211
	v_exp_f32_e32 v122, v122
	v_exp_f32_e32 v123, v123
	v_exp_f32_e32 v124, v124
	v_exp_f32_e32 v125, v125
	v_exp_f32_e32 v126, v126
	v_exp_f32_e32 v127, v127
	v_exp_f32_e32 v128, v128
	v_exp_f32_e32 v129, v129
	v_cvt_pk_bf16_f32 v212, v130, v131
	v_cvt_pk_bf16_f32 v213, v132, v133
	v_cvt_pk_bf16_f32 v214, v134, v135
	v_cvt_pk_bf16_f32 v215, v136, v137
	v_cvt_pk_bf16_f32 v216, v138, v139
	v_cvt_pk_bf16_f32 v217, v140, v141
	v_cvt_pk_bf16_f32 v218, v142, v143
	v_cvt_pk_bf16_f32 v219, v144, v145
	v_cvt_pk_bf16_f32 v220, v114, v115
	v_cvt_pk_bf16_f32 v221, v116, v117
	v_cvt_pk_bf16_f32 v222, v118, v119
	v_cvt_pk_bf16_f32 v223, v120, v121
	v_cvt_pk_bf16_f32 v224, v122, v123
	v_cvt_pk_bf16_f32 v225, v124, v125
	v_cvt_pk_bf16_f32 v226, v126, v127
	v_cvt_pk_bf16_f32 v227, v128, v129
.Lnw_xdone:
	s_waitcnt lgkmcnt(0)
	s_barrier
	s_setprio 3
	s_add_i32 s26, s13, 1
	s_mov_b32 s17, 0
	s_cmp_ge_u32 s26, s12
	s_cbranch_scc1 .Lnw_y1
	s_add_i32 s15, s14, 1

;     ...
;             const int k0 = j * 64;
;             if (k0 > qb + 31 || k0 + 63 <= qb - 512) return;
	s_lshl_b32 s6, s15, 6
	s_add_i32 s7, s21, 31
	s_cmp_le_i32 s6, s7
	s_cselect_b32 s17, 1, 0
	s_add_i32 s6, s6, 63
	s_add_i32 s7, s21, 0xfffffe00
	s_cmp_gt_i32 s6, s7
	s_cselect_b32 s7, 1, 0
	s_and_b32 s17, s17, s7

;     ...
;             const int k0 = j * 64;
;             if (k0 > qb + 31 || k0 + 63 <= qb - 512) return;
;             f32x16 s0, s1; attn_scores(sb, qf, r, h, s0, s1);
.Lnw_y1:
	v_add3_u32 v237, s18, v204, v180
	v_add3_u32 v236, s19, v204, v180
	s_cmp_eq_u32 s16, 0
	s_cbranch_scc1 .Lnw_noa
	s_cmp_eq_u32 s17, 0
	s_cbranch_scc1 .Lnw_pvonly

; #define MFMA(a, b, c) __builtin_amdgcn_mfma_f32_32x32x16_bf16((a), (b), (c), 0, 0, 0)
; DI void attn_scores(const unsigned char* kb, const bf16x8 (&qf)[4], int r, int h, f32x16& s0, f32x16& s1) {
; #pragma unroll
;     for (int i = 0; i < 16; ++i) { s0[i] = 0.f; s1[i] = 0.f; }
; #pragma unroll
;     for (int s = 0; s < 4; ++s) {
;         const bf16x8 k0 = *(const bf16x8*)(kb + r * KP + s * 32 + h * 16);
;         const bf16x8 k1 = *(const bf16x8*)(kb + (32 + r) * KP + s * 32 + h * 16);
;         s0 = MFMA(k0, qf[s], s0); s1 = MFMA(k1, qf[s], s1);
;     }
; }
; template <int DV>
; DI void attn_pv(const unsigned char* vb, const bf16x8 (&pf)[2][2], int r, int h, f32x16 (&o)[DV / 32]) {
; #pragma unroll
;     for (int dt = 0; dt < DV / 32; ++dt)
; #pragma unroll
;         for (int mt = 0; mt < 2; ++mt)
; #pragma unroll
;             for (int sp = 0; sp < 2; ++sp) {
;                 const bf16x8 vf = *(const bf16x8*)(vb + (dt * 32 + r) * VP + (2 * mt + sp) * 32 + h * 16);
;                 o[dt] = MFMA(vf, pf[mt][sp], o[dt]);
;             }
; }
	ds_read_b128 v[228:231], v237 offset:9216
	ds_read_b128 v[232:235], v237 offset:9248
	ds_read_b128 v[206:209], v237 offset:9280
	s_waitcnt lgkmcnt(2)
	v_mfma_f32_32x32x16_bf16 v[82:97], v[228:231], v[212:215], v[82:97]
	ds_read_b128 v[228:231], v237 offset:9312
	v_add_f32_e32 v130, v130, v114
	v_add_f32_e32 v131, v131, v115
	v_add_f32_e32 v98, v98, v130
	v_add_f32_e32 v132, v132, v116
	s_waitcnt lgkmcnt(2)
	v_mfma_f32_32x32x16_bf16 v[82:97], v[232:235], v[216:219], v[82:97]
	ds_read_b128 v[232:235], v237 offset:13824
	v_add_f32_e32 v99, v99, v131
	v_add_f32_e32 v133, v133, v117
	v_add_f32_e32 v100, v100, v132
	v_add_f32_e32 v134, v134, v118
	s_waitcnt lgkmcnt(2)
	v_mfma_f32_32x32x16_bf16 v[82:97], v[206:209], v[220:223], v[82:97]
	ds_read_b128 v[206:209], v237 offset:13856
	v_add_f32_e32 v101, v101, v133
	v_add_f32_e32 v135, v135, v119
	v_add_f32_e32 v102, v102, v134
	v_add_f32_e32 v136, v136, v120
	s_waitcnt lgkmcnt(2)
	v_mfma_f32_32x32x16_bf16 v[82:97], v[228:231], v[224:227], v[82:97]
	ds_read_b128 v[228:231], v237 offset:13888
	v_add_f32_e32 v103, v103, v135
	v_add_f32_e32 v137, v137, v121
	v_add_f32_e32 v104, v104, v136
	v_add_f32_e32 v138, v138, v122
	s_waitcnt lgkmcnt(2)
	v_mfma_f32_32x32x16_bf16 v[66:81], v[232:235], v[212:215], v[66:81]
	ds_read_b128 v[232:235], v237 offset:13920
	v_add_f32_e32 v105, v105, v137
	v_add_f32_e32 v139, v139, v123
	v_add_f32_e32 v106, v106, v138
	v_add_f32_e32 v140, v140, v124
	s_waitcnt lgkmcnt(2)
	v_mfma_f32_32x32x16_bf16 v[66:81], v[206:209], v[216:219], v[66:81]
	ds_read_b128 v[206:209], v236 offset:0
	v_add_f32_e32 v107, v107, v139
	v_add_f32_e32 v141, v141, v125
	v_add_f32_e32 v108, v108, v140
	v_add_f32_e32 v142, v142, v126
	s_waitcnt lgkmcnt(2)
	v_mfma_f32_32x32x16_bf16 v[66:81], v[228:231], v[220:223], v[66:81]
	ds_read_b128 v[228:231], v236 offset:4608
	v_add_f32_e32 v109, v109, v141
	v_add_f32_e32 v143, v143, v127
	v_add_f32_e32 v110, v110, v142
	v_add_f32_e32 v144, v144, v128
	s_waitcnt lgkmcnt(2)
	v_mfma_f32_32x32x16_bf16 v[66:81], v[232:235], v[224:227], v[66:81]
	ds_read_b128 v[232:235], v236 offset:32
	v_add_f32_e32 v111, v111, v143
	v_add_f32_e32 v145, v145, v129
	v_add_f32_e32 v112, v112, v144
	v_add_f32_e32 v113, v113, v145
	s_waitcnt lgkmcnt(2)
	v_mfma_f32_32x32x16_bf16 v[130:145], v[206:209], v[146:149], 0
	ds_read_b128 v[206:209], v236 offset:4640
	s_waitcnt lgkmcnt(2)
	v_mfma_f32_32x32x16_bf16 v[114:129], v[228:231], v[146:149], 0
	ds_read_b128 v[228:231], v236 offset:64
	s_waitcnt lgkmcnt(2)
	v_mfma_f32_32x32x16_bf16 v[130:145], v[232:235], v[150:153], v[130:145]
	ds_read_b128 v[232:235], v236 offset:4672
	s_waitcnt lgkmcnt(2)
	v_mfma_f32_32x32x16_bf16 v[114:129], v[206:209], v[150:153], v[114:129]
	ds_read_b128 v[206:209], v236 offset:96
	s_waitcnt lgkmcnt(2)
	v_mfma_f32_32x32x16_bf16 v[130:145], v[228:231], v[154:157], v[130:145]
	ds_read_b128 v[228:231], v236 offset:4704
	s_waitcnt lgkmcnt(2)
	v_mfma_f32_32x32x16_bf16 v[114:129], v[232:235], v[154:157], v[114:129]
	s_waitcnt lgkmcnt(1)
	v_mfma_f32_32x32x16_bf16 v[130:145], v[206:209], v[158:161], v[130:145]
	s_waitcnt lgkmcnt(0)
	v_mfma_f32_32x32x16_bf16 v[114:129], v[228:231], v[158:161], v[114:129]
	s_branch .Lnw_stage
.Lnw_pvonly:
	ds_read_b128 v[228:231], v237 offset:9216
	ds_read_b128 v[232:235], v237 offset:9248
	ds_read_b128 v[206:209], v237 offset:9280
	s_waitcnt lgkmcnt(2)
	v_mfma_f32_32x32x16_bf16 v[82:97], v[228:231], v[212:215], v[82:97]
	ds_read_b128 v[228:231], v237 offset:9312
	v_add_f32_e32 v130, v130, v114
	v_add_f32_e32 v131, v131, v115
	v_add_f32_e32 v98, v98, v130
	v_add_f32_e32 v132, v132, v116
	s_waitcnt lgkmcnt(2)
	v_mfma_f32_32x32x16_bf16 v[82:97], v[232:235], v[216:219], v[82:97]
	ds_read_b128 v[232:235], v237 offset:13824
	v_add_f32_e32 v99, v99, v131
	v_add_f32_e32 v133, v133, v117
	v_add_f32_e32 v100, v100, v132
	v_add_f32_e32 v134, v134, v118
	s_waitcnt lgkmcnt(2)
	v_mfma_f32_32x32x16_bf16 v[82:97], v[206:209], v[220:223], v[82:97]
	ds_read_b128 v[206:209], v237 offset:13856
	v_add_f32_e32 v101, v101, v133
	v_add_f32_e32 v135, v135, v119
	v_add_f32_e32 v102, v102, v134
	v_add_f32_e32 v136, v136, v120
	s_waitcnt lgkmcnt(2)
	v_mfma_f32_32x32x16_bf16 v[82:97], v[228:231], v[224:227], v[82:97]
	ds_read_b128 v[228:231], v237 offset:13888
	v_add_f32_e32 v103, v103, v135
	v_add_f32_e32 v137, v137, v121
	v_add_f32_e32 v104, v104, v136
	v_add_f32_e32 v138, v138, v122
	s_waitcnt lgkmcnt(2)
	v_mfma_f32_32x32x16_bf16 v[66:81], v[232:235], v[212:215], v[66:81]
	ds_read_b128 v[232:235], v237 offset:13920
	v_add_f32_e32 v105, v105, v137
	v_add_f32_e32 v139, v139, v123
	v_add_f32_e32 v106, v106, v138
	v_add_f32_e32 v140, v140, v124
	s_waitcnt lgkmcnt(2)
	v_mfma_f32_32x32x16_bf16 v[66:81], v[206:209], v[216:219], v[66:81]
	v_add_f32_e32 v107, v107, v139
	v_add_f32_e32 v141, v141, v125
	v_add_f32_e32 v108, v108, v140
	v_add_f32_e32 v142, v142, v126
	s_waitcnt lgkmcnt(1)
	v_mfma_f32_32x32x16_bf16 v[66:81], v[228:231], v[220:223], v[66:81]
	v_add_f32_e32 v109, v109, v141
	v_add_f32_e32 v143, v143, v127
	v_add_f32_e32 v110, v110, v142
	v_add_f32_e32 v144, v144, v128
	s_waitcnt lgkmcnt(0)
	v_mfma_f32_32x32x16_bf16 v[66:81], v[232:235], v[224:227], v[66:81]
	v_add_f32_e32 v111, v111, v143
	v_add_f32_e32 v145, v145, v129
	v_add_f32_e32 v112, v112, v144
	v_add_f32_e32 v113, v113, v145
	s_branch .Lnw_stage
